# first grid sync (after phase 0) replaced by a self-initialising XCD-hierarchical barrier (state in the y rows, zeroed by block 0 with atomics)
# speedup vs baseline: 1.0115x; 1.0104x over previous
; #define RUN_PHASE(k, fn)                                  \
;   if (ph_lo <= k && k <= ph_hi) {                         \
;     if (k == PROBE_DUP) { fn(p, smem); cg::this_grid().sync(); } \
;     fn(p, smem);                                          \
;     if (k < ph_hi) cg::this_grid().sync();                \
;   }
; __device__ void phase0(const Params& p, unsigned char* smem) {
;   const int tid = threadIdx.x;
;   unsigned char* ws = p.ws;
;   float* smf = (float*)smem;
;   const int NT_IN = 92 * 16, NT_OA = 16 * 8, NT_OUT = 16 * 16, NT_UP = 64 * 16, NT_DN = 16 * 64;
;   const int total = NT_IN + 2 * NT_OA + NT_OUT + NT_UP + NT_DN;
;   {
;     const int lane_ = tid & 63, wave_ = tid >> 6;
;     float* smw = smf + wave_ * (64 * 65);
;     for (int t = blockIdx.x * 8 + wave_; t < total; t += gridDim.x * 8) {
;       int u = t;
;       const float* src; int ld, k0, nsrc0, nvalid = 64, K, ndst0, permg = -1; u16* dst; const float* gain = nullptr;
; __global__ void __launch_bounds__(512) mega(Params p, int ph_lo, int ph_hi) {
;   __shared__ __align__(16) unsigned char smem[SMEM_BYTES];
;     ...
;   RUN_PHASE(0, phase0)
;   RUN_PHASE(1, phase1)
_Z4mega6Paramsii:
	s_mov_b32 s94, s2
	s_mov_b64 s[92:93], s[0:1]
	s_load_dwordx8 s[84:91], s[0:1], 0xa0
	s_nop 0
	s_load_dwordx16 s[0:15], s[92:93], 0x0
	s_load_dwordx8 s[52:59], s[92:93], 0x80
	s_waitcnt lgkmcnt(0)
	s_cmp_gt_i32 s90, 0
	v_writelane_b32 v239, s0, 0
	s_nop 1
	v_writelane_b32 v239, s1, 1
	v_writelane_b32 v239, s2, 2
	v_writelane_b32 v239, s3, 3
	v_writelane_b32 v239, s4, 4
	v_writelane_b32 v239, s5, 5
	v_writelane_b32 v239, s6, 6
	v_writelane_b32 v239, s7, 7
	v_writelane_b32 v239, s8, 8
	v_writelane_b32 v239, s9, 9
	v_writelane_b32 v239, s10, 10
	v_writelane_b32 v239, s11, 11
	v_writelane_b32 v239, s12, 12
	v_writelane_b32 v239, s13, 13
	v_writelane_b32 v239, s14, 14
	v_writelane_b32 v239, s15, 15
	s_load_dwordx16 s[4:19], s[92:93], 0x40
	s_cselect_b64 s[0:1], -1, 0
	s_cmp_lt_i32 s91, 0
	s_waitcnt lgkmcnt(0)
	v_writelane_b32 v239, s4, 16
	s_nop 1
	v_writelane_b32 v239, s5, 17
	v_writelane_b32 v239, s6, 18
	v_writelane_b32 v239, s7, 19
	v_writelane_b32 v239, s8, 20
	v_writelane_b32 v239, s9, 21
	v_writelane_b32 v239, s10, 22
	v_writelane_b32 v239, s11, 23
	v_writelane_b32 v239, s12, 24
	v_writelane_b32 v239, s13, 25
	v_writelane_b32 v239, s14, 26
	v_writelane_b32 v239, s15, 27
	v_writelane_b32 v239, s16, 28
	v_writelane_b32 v239, s17, 29
	v_writelane_b32 v239, s18, 30
	v_writelane_b32 v239, s19, 31
	s_cselect_b64 s[4:5], -1, 0
	s_or_b64 s[0:1], s[0:1], s[4:5]
	s_and_b64 vcc, exec, s[0:1]
	s_cbranch_vccnz .LBB0_219
	s_cmp_lg_u32 s94, 0
	s_cbranch_scc1 .Lgbf_noinit
	v_cmp_gt_u32_e32 vcc, 26, v0
	s_and_saveexec_b64 s[4:5], vcc
	v_lshlrev_b32_e32 v1, 8, v0
	v_mov_b32_e32 v2, 0
	global_atomic_and v1, v2, s[86:87]
	s_mov_b64 exec, s[4:5]
.Lgbf_noinit:
	v_bfe_u32 v2, v0, 6, 4
	v_lshl_or_b32 v34, s94, 3, v2
	s_movk_i32 s0, 0xfbf
	v_cmp_lt_i32_e32 vcc, s0, v34
	s_and_saveexec_b64 s[6:7], vcc
	s_xor_b64 s[6:7], exec, s[6:7]
	s_load_dword s0, s[92:93], 0xc0
	s_add_u32 s4, s92, 0xc0
	s_addc_u32 s5, s93, 0
	s_or_saveexec_b64 s[60:61], s[6:7]
	v_and_b32_e32 v4, 63, v0
	v_mov_b64_e32 v[40:41], s[4:5]
	s_waitcnt lgkmcnt(0)
	v_mov_b32_e32 v1, s0
	s_xor_b64 exec, exec, s[60:61]
	s_cbranch_execz .LBB0_163
	s_add_u32 s62, s88, 0x1780000
	s_addc_u32 s63, s89, 0
	s_add_u32 s64, s88, 0xf80000
	s_addc_u32 s65, s89, 0
	s_add_u32 s66, s88, 0xd80000
	s_addc_u32 s67, s89, 0
	s_add_u32 s24, s88, 0xc80000
	s_load_dword s0, s[92:93], 0xc0
	s_addc_u32 s25, s89, 0
	s_add_u32 s26, s88, 0xb80000
	v_mul_u32_u24_e32 v1, 0x4100, v2
	s_addc_u32 s27, s89, 0
	s_movk_i32 s1, 0x4100
	v_mov_b32_e32 v7, 0
	v_lshl_or_b32 v13, v4, 2, v1
	v_mul_u32_u24_e32 v1, 0x104, v4
	s_add_u32 s28, s92, 0xc0
	v_cmp_gt_u32_e64 s[4:5], 8, v4
	v_mad_u32_u24 v24, v2, s1, v1
	s_addc_u32 s29, s93, 0
	s_waitcnt lgkmcnt(0)
	s_lshl_b32 s1, s0, 3
	s_mov_b64 s[30:31], 0
	s_movk_i32 s3, 0x5bf
	s_movk_i32 s33, 0x63f
	s_movk_i32 s46, 0x6bf
	s_movk_i32 s47, 0x7bf
	s_movk_i32 s48, 0xbbf
	s_mov_b32 s34, 31
	s_movk_i32 s49, 0x20f
	s_movk_i32 s50, 0x59
	s_movk_i32 s51, 0x5a0
	s_movk_i32 s68, 0x590
	v_lshlrev_b32_e32 v8, 2, v4
	v_mov_b32_e32 v9, v7
	s_movk_i32 s69, 0x60
	s_movk_i32 s36, 0x80
	s_movk_i32 s70, 0x7fff
	s_movk_i32 s71, 0xfbf
	v_mov_b32_e32 v25, 0x840
	v_mov_b32_e32 v26, 1
	v_mov_b32_e32 v27, v34

; #define RUN_PHASE(k, fn)                                  \
;   if (ph_lo <= k && k <= ph_hi) {                         \
;     if (k == PROBE_DUP) { fn(p, smem); cg::this_grid().sync(); } \
;     fn(p, smem);                                          \
;     if (k < ph_hi) cg::this_grid().sync();                \
;   }
; __global__ void __launch_bounds__(512) mega(Params p, int ph_lo, int ph_hi) {
;     ...
;   RUN_PHASE(0, phase0)
;   RUN_PHASE(1, phase1)
.LBB0_207:
	s_or_b64 exec, exec, s[6:7]
	s_cmp_lt_i32 s91, 1
	s_cbranch_scc1 .LBB0_219
	s_waitcnt vmcnt(0) lgkmcnt(0)
	s_barrier
	v_cmp_eq_u32_e32 vcc, 0, v0
	s_and_saveexec_b64 s[4:5], vcc
	s_cbranch_execz .Lgbf_done
	v_mov_b32_e32 v10, 0
	v_mov_b32_e32 v11, 1
	s_load_dword s10, s[92:93], 0xc0
	s_getreg_b32 s100, hwreg(HW_REG_XCC_ID, 0, 4)
	v_mov_b32_e32 v9, 0x1900
	s_and_b32 s100, s100, 7
	s_cmp_lg_u32 s94, 0
	s_cbranch_scc1 .Lgbf_rdy_init
	v_mov_b32_e32 v1, 0x5a17c0de
	global_atomic_swap v9, v1, s[86:87]

.Lgbf_rdy:
	global_atomic_add v2, v9, v10, s[86:87] sc0
	s_waitcnt vmcnt(0)
	v_readfirstlane_b32 s7, v2
	s_cmp_eq_u32 s7, 0x5a17c0de
	s_cbranch_scc1 .Lgbf_rdy_ok
	s_sleep 1
	s_sub_i32 s11, s11, 1
	s_cmp_lg_u32 s11, 0
	s_cbranch_scc1 .Lgbf_rdy
.Lgbf_rdy_ok:
	s_lshl_b32 s0, s100, 8
	v_mov_b32_e32 v1, s0
	global_atomic_add v1, v11, s[86:87]
	s_movk_i32 s11, 0x800
.Lgbf_census:
	global_atomic_add v1, v10, v10, s[86:87] offset:0 sc0
	global_atomic_add v2, v10, v10, s[86:87] offset:256 sc0
	global_atomic_add v3, v10, v10, s[86:87] offset:512 sc0
	global_atomic_add v4, v10, v10, s[86:87] offset:768 sc0
	global_atomic_add v5, v10, v10, s[86:87] offset:1024 sc0
	global_atomic_add v6, v10, v10, s[86:87] offset:1280 sc0
	global_atomic_add v7, v10, v10, s[86:87] offset:1536 sc0
	global_atomic_add v8, v10, v10, s[86:87] offset:1792 sc0
	s_waitcnt vmcnt(0) lgkmcnt(0)
	v_readfirstlane_b32 s12, v1
	v_readfirstlane_b32 s13, v2
	v_readfirstlane_b32 s14, v3
	v_readfirstlane_b32 s15, v4
	v_readfirstlane_b32 s16, v5
	v_readfirstlane_b32 s17, v6
	v_readfirstlane_b32 s18, v7
	v_readfirstlane_b32 s19, v8
	s_mov_b32 s20, 0
	s_mov_b32 s21, 0
	s_add_i32 s20, s20, s12
	s_cmp_lg_u32 s12, 0
	s_addc_u32 s21, s21, 0
	s_add_i32 s20, s20, s13
	s_cmp_lg_u32 s13, 0
	s_addc_u32 s21, s21, 0
	s_add_i32 s20, s20, s14
	s_cmp_lg_u32 s14, 0
	s_addc_u32 s21, s21, 0
	s_add_i32 s20, s20, s15
	s_cmp_lg_u32 s15, 0
	s_addc_u32 s21, s21, 0
	s_add_i32 s20, s20, s16
	s_cmp_lg_u32 s16, 0
	s_addc_u32 s21, s21, 0
	s_add_i32 s20, s20, s17
	s_cmp_lg_u32 s17, 0
	s_addc_u32 s21, s21, 0
	s_add_i32 s20, s20, s18
	s_cmp_lg_u32 s18, 0
	s_addc_u32 s21, s21, 0
	s_add_i32 s20, s20, s19
	s_cmp_lg_u32 s19, 0
	s_addc_u32 s21, s21, 0
	s_cmp_eq_u32 s20, s10
	s_cbranch_scc1 .Lgbf_census_ok
	s_sleep 2
	s_sub_i32 s11, s11, 1
	s_cmp_lg_u32 s11, 0
	s_cbranch_scc1 .Lgbf_census
.Lgbf_census_ok:
	s_mov_b32 s98, s12
	s_cmp_eq_u32 s100, 1
	s_cselect_b32 s98, s13, s98
	s_cmp_eq_u32 s100, 2
	s_cselect_b32 s98, s14, s98
	s_cmp_eq_u32 s100, 3
	s_cselect_b32 s98, s15, s98
	s_cmp_eq_u32 s100, 4
	s_cselect_b32 s98, s16, s98
	s_cmp_eq_u32 s100, 5
	s_cselect_b32 s98, s17, s98
	s_cmp_eq_u32 s100, 6
	s_cselect_b32 s98, s18, s98
	s_cmp_eq_u32 s100, 7
	s_cselect_b32 s98, s19, s98
	s_max_u32 s98, s98, 1
	s_max_u32 s99, s21, 1
	s_add_i32 s1, s0, 0x800
	v_mov_b32_e32 v1, s1
	global_atomic_add v2, v1, v11, s[86:87] sc0
	s_add_i32 s2, s0, 0x1000
	s_waitcnt vmcnt(0)
	v_readfirstlane_b32 s7, v2
	s_cmp_eq_u32 s7, 0
	s_cbranch_scc0 .Lgbf_wait
	buffer_wbl2 sc1
	s_waitcnt vmcnt(0)
	v_mov_b32_e32 v1, 0x1800
	global_atomic_add v2, v1, v11, s[86:87] sc0
	s_waitcnt vmcnt(0)
	v_readfirstlane_b32 s7, v2
	s_add_i32 s7, s7, 1
	s_cmp_eq_u32 s7, s99
	s_cbranch_scc0 .Lgbf_wait
	v_mov_b32_e32 v12, 0x1000
	global_atomic_add v12, v11, s[86:87]
	global_atomic_add v12, v11, s[86:87] offset:256
	global_atomic_add v12, v11, s[86:87] offset:512
	global_atomic_add v12, v11, s[86:87] offset:768
	global_atomic_add v12, v11, s[86:87] offset:1024
	global_atomic_add v12, v11, s[86:87] offset:1280
	global_atomic_add v12, v11, s[86:87] offset:1536
	global_atomic_add v12, v11, s[86:87] offset:1792

.Lgbf_spin:
	global_atomic_add v2, v1, v10, s[86:87] sc0
	s_waitcnt vmcnt(0)
	v_readfirstlane_b32 s7, v2
	s_cmp_gt_u32 s7, 0
	s_cbranch_scc1 .Lgbf_acq
	s_sleep 1
	s_sub_i32 s11, s11, 1
	s_cmp_lg_u32 s11, 0
	s_cbranch_scc1 .Lgbf_spin

; #define RUN_PHASE(k, fn)                                  \
;   if (ph_lo <= k && k <= ph_hi) {                         \
;     if (k == PROBE_DUP) { fn(p, smem); cg::this_grid().sync(); } \
;     fn(p, smem);                                          \
;     if (k < ph_hi) cg::this_grid().sync();                \
;   }
; __global__ void __launch_bounds__(512) mega(Params p, int ph_lo, int ph_hi) {
;     ...
;   RUN_PHASE(0, phase0)
;   RUN_PHASE(1, phase1)
.LBB0_512:
	s_cmp_lt_i32 s91, 2
	s_cbranch_scc1 .LBB0_524
	s_waitcnt vmcnt(0) lgkmcnt(0)
	s_barrier
	v_cmp_eq_u32_e32 vcc, 0, v0
	s_and_saveexec_b64 s[4:5], vcc
	s_cbranch_execz .Lgb0_done
	s_add_u32 s8, s88, 0xb20000
	s_addc_u32 s9, s89, 0
	v_mov_b32_e32 v10, 0
	v_mov_b32_e32 v11, 1
	s_lshl_b32 s0, s100, 8
	s_add_i32 s1, s0, 0x1000
	v_mov_b32_e32 v1, s1
	global_atomic_add v2, v1, v11, s[8:9] sc0
	s_add_i32 s2, s0, 0x2000
	s_mul_i32 s3, s98, 1
	s_mul_i32 s6, s99, 1
	s_waitcnt vmcnt(0)
	v_readfirstlane_b32 s7, v2
	s_add_i32 s7, s7, 1
	s_cmp_eq_u32 s7, s3
	s_cbranch_scc0 .Lgb0_wait
	buffer_wbl2 sc1
	s_waitcnt vmcnt(0)
	v_mov_b32_e32 v1, 0x3000
	global_atomic_add v2, v1, v11, s[8:9] sc0
	s_waitcnt vmcnt(0)
	v_readfirstlane_b32 s7, v2
	s_add_i32 s7, s7, 1
	v_mov_b32_e32 v1, 0x3100
	s_cmp_eq_u32 s7, s6
	s_cbranch_scc0 .Lgb0_wait
	v_mov_b32_e32 v12, 0x2000
	global_atomic_add v12, v11, s[8:9]
	global_atomic_add v12, v11, s[8:9] offset:256
	global_atomic_add v12, v11, s[8:9] offset:512
	global_atomic_add v12, v11, s[8:9] offset:768
	global_atomic_add v12, v11, s[8:9] offset:1024
	global_atomic_add v12, v11, s[8:9] offset:1280
	global_atomic_add v12, v11, s[8:9] offset:1536
	global_atomic_add v12, v11, s[8:9] offset:1792
